# v2 + nt (non-temporal) hint on the once-read f32 input loads of the prologue (weights, x) so they do not displace the bf16 copies the next phase reads
# speedup vs baseline: 1.0170x; 1.0115x over previous
.Lpa_s0_gd:
	s_add_u32 s100, s66, 6
	s_lshl_b32 s100, s3, s100
	s_lshl_b32 s101, s28, 1
	s_add_u32 s100, s100, s101
	s_add_u32 s100, s100, s97
	s_add_u32 s62, s34, s100
	s_addc_u32 s63, s35, 0
	global_load_dword v10, v4, s[60:61] nt
	s_add_u32 s60, s60, s67
	s_addc_u32 s61, s61, 0
	global_load_dword v11, v4, s[60:61] nt
	s_add_u32 s60, s60, s67
	s_addc_u32 s61, s61, 0
	global_load_dword v12, v4, s[60:61] nt
	s_add_u32 s60, s60, s67
	s_addc_u32 s61, s61, 0
	global_load_dword v13, v4, s[60:61] nt
	s_add_u32 s60, s60, s67
	s_addc_u32 s61, s61, 0
	global_load_dword v14, v4, s[60:61] nt
	s_add_u32 s60, s60, s67
	s_addc_u32 s61, s61, 0
	global_load_dword v15, v4, s[60:61] nt
	s_add_u32 s60, s60, s67
	s_addc_u32 s61, s61, 0
	global_load_dword v16, v4, s[60:61] nt
	s_add_u32 s60, s60, s67
	s_addc_u32 s61, s61, 0
	global_load_dword v17, v4, s[60:61] nt
	s_lshl_b32 s0, s84, 2
	s_add_u32 s0, s0, 1
	s_mul_i32 s0, s0, s86
	s_add_u32 s3, s0, s2
	s_sub_u32 s0, s3, s86
	s_cmp_ge_u32 s3, 6480
	s_cselect_b32 s3, s0, s3
	s_sub_u32 s0, s3, s86
	s_cmp_ge_u32 s3, 6480
	s_cselect_b32 s3, s0, s3
	s_sub_u32 s0, s3, s86
	s_cmp_ge_u32 s3, 6480
	s_cselect_b32 s3, s0, s3
	s_cmp_ge_u32 s3, 5456
	s_cbranch_scc1 .Lpa_s1_j15
	s_cmp_ge_u32 s3, 4432
	s_cbranch_scc1 .Lpa_s1_j14
	s_cmp_ge_u32 s3, 3920
	s_cbranch_scc1 .Lpa_s1_j13
	s_cmp_ge_u32 s3, 3728
	s_cbranch_scc1 .Lpa_s1_j12
	s_cmp_ge_u32 s3, 3600
	s_cbranch_scc1 .Lpa_s1_j11
	s_cmp_ge_u32 s3, 3472
	s_cbranch_scc1 .Lpa_s1_j10
	s_cmp_ge_u32 s3, 3408
	s_cbranch_scc1 .Lpa_s1_j9
	s_cmp_ge_u32 s3, 3392
	s_cbranch_scc1 .Lpa_s1_j8
	s_cmp_ge_u32 s3, 3328
	s_cbranch_scc1 .Lpa_s1_j7
	s_cmp_ge_u32 s3, 2304
	s_cbranch_scc1 .Lpa_s1_j6
	s_cmp_ge_u32 s3, 1280
	s_cbranch_scc1 .Lpa_s1_j5
	s_cmp_ge_u32 s3, 1024
	s_cbranch_scc1 .Lpa_s1_j4
	s_cmp_ge_u32 s3, 768
	s_cbranch_scc1 .Lpa_s1_j3
	s_cmp_ge_u32 s3, 512
	s_cbranch_scc1 .Lpa_s1_j2
	s_cmp_ge_u32 s3, 256
	s_cbranch_scc1 .Lpa_s1_j1
	s_branch .Lpa_s1_j0

.Lpa_s1_gd:
	s_add_u32 s100, s74, 6
	s_lshl_b32 s100, s3, s100
	s_lshl_b32 s101, s28, 1
	s_add_u32 s100, s100, s101
	s_add_u32 s100, s100, s97
	s_add_u32 s70, s34, s100
	s_addc_u32 s71, s35, 0
	global_load_dword v18, v4, s[68:69] nt
	s_add_u32 s68, s68, s75
	s_addc_u32 s69, s69, 0
	global_load_dword v19, v4, s[68:69] nt
	s_add_u32 s68, s68, s75
	s_addc_u32 s69, s69, 0
	global_load_dword v20, v4, s[68:69] nt
	s_add_u32 s68, s68, s75
	s_addc_u32 s69, s69, 0
	global_load_dword v21, v4, s[68:69] nt
	s_add_u32 s68, s68, s75
	s_addc_u32 s69, s69, 0
	global_load_dword v22, v4, s[68:69] nt
	s_add_u32 s68, s68, s75
	s_addc_u32 s69, s69, 0
	global_load_dword v23, v4, s[68:69] nt
	s_add_u32 s68, s68, s75
	s_addc_u32 s69, s69, 0
	global_load_dword v24, v4, s[68:69] nt
	s_add_u32 s68, s68, s75
	s_addc_u32 s69, s69, 0
	global_load_dword v25, v4, s[68:69] nt
	s_lshl_b32 s0, s84, 2
	s_add_u32 s0, s0, 2
	s_mul_i32 s0, s0, s86
	s_add_u32 s3, s0, s2
	s_sub_u32 s0, s3, s86
	s_cmp_ge_u32 s3, 6480
	s_cselect_b32 s3, s0, s3
	s_sub_u32 s0, s3, s86
	s_cmp_ge_u32 s3, 6480
	s_cselect_b32 s3, s0, s3
	s_sub_u32 s0, s3, s86
	s_cmp_ge_u32 s3, 6480
	s_cselect_b32 s3, s0, s3
	s_cmp_ge_u32 s3, 5456
	s_cbranch_scc1 .Lpa_s2_j15
	s_cmp_ge_u32 s3, 4432
	s_cbranch_scc1 .Lpa_s2_j14
	s_cmp_ge_u32 s3, 3920
	s_cbranch_scc1 .Lpa_s2_j13
	s_cmp_ge_u32 s3, 3728
	s_cbranch_scc1 .Lpa_s2_j12
	s_cmp_ge_u32 s3, 3600
	s_cbranch_scc1 .Lpa_s2_j11
	s_cmp_ge_u32 s3, 3472
	s_cbranch_scc1 .Lpa_s2_j10
	s_cmp_ge_u32 s3, 3408
	s_cbranch_scc1 .Lpa_s2_j9
	s_cmp_ge_u32 s3, 3392
	s_cbranch_scc1 .Lpa_s2_j8
	s_cmp_ge_u32 s3, 3328
	s_cbranch_scc1 .Lpa_s2_j7
	s_cmp_ge_u32 s3, 2304
	s_cbranch_scc1 .Lpa_s2_j6
	s_cmp_ge_u32 s3, 1280
	s_cbranch_scc1 .Lpa_s2_j5
	s_cmp_ge_u32 s3, 1024
	s_cbranch_scc1 .Lpa_s2_j4
	s_cmp_ge_u32 s3, 768
	s_cbranch_scc1 .Lpa_s2_j3
	s_cmp_ge_u32 s3, 512
	s_cbranch_scc1 .Lpa_s2_j2
	s_cmp_ge_u32 s3, 256
	s_cbranch_scc1 .Lpa_s2_j1
	s_branch .Lpa_s2_j0

.Lpa_s2_gd:
	s_add_u32 s100, s82, 6
	s_lshl_b32 s100, s3, s100
	s_lshl_b32 s101, s28, 1
	s_add_u32 s100, s100, s101
	s_add_u32 s100, s100, s97
	s_add_u32 s78, s34, s100
	s_addc_u32 s79, s35, 0
	global_load_dword v26, v4, s[76:77] nt
	s_add_u32 s76, s76, s83
	s_addc_u32 s77, s77, 0
	global_load_dword v27, v4, s[76:77] nt
	s_add_u32 s76, s76, s83
	s_addc_u32 s77, s77, 0
	global_load_dword v28, v4, s[76:77] nt
	s_add_u32 s76, s76, s83
	s_addc_u32 s77, s77, 0
	global_load_dword v29, v4, s[76:77] nt
	s_add_u32 s76, s76, s83
	s_addc_u32 s77, s77, 0
	global_load_dword v30, v4, s[76:77] nt
	s_add_u32 s76, s76, s83
	s_addc_u32 s77, s77, 0
	global_load_dword v31, v4, s[76:77] nt
	s_add_u32 s76, s76, s83
	s_addc_u32 s77, s77, 0
	global_load_dword v32, v4, s[76:77] nt
	s_add_u32 s76, s76, s83
	s_addc_u32 s77, s77, 0
	global_load_dword v33, v4, s[76:77] nt
	s_lshl_b32 s0, s84, 2
	s_add_u32 s0, s0, 3
	s_mul_i32 s0, s0, s86
	s_add_u32 s3, s0, s2
	s_sub_u32 s0, s3, s86
	s_cmp_ge_u32 s3, 6480
	s_cselect_b32 s3, s0, s3
	s_sub_u32 s0, s3, s86
	s_cmp_ge_u32 s3, 6480
	s_cselect_b32 s3, s0, s3
	s_sub_u32 s0, s3, s86
	s_cmp_ge_u32 s3, 6480
	s_cselect_b32 s3, s0, s3
	s_cmp_ge_u32 s3, 5456
	s_cbranch_scc1 .Lpa_s3_j15
	s_cmp_ge_u32 s3, 4432
	s_cbranch_scc1 .Lpa_s3_j14
	s_cmp_ge_u32 s3, 3920
	s_cbranch_scc1 .Lpa_s3_j13
	s_cmp_ge_u32 s3, 3728
	s_cbranch_scc1 .Lpa_s3_j12
	s_cmp_ge_u32 s3, 3600
	s_cbranch_scc1 .Lpa_s3_j11
	s_cmp_ge_u32 s3, 3472
	s_cbranch_scc1 .Lpa_s3_j10
	s_cmp_ge_u32 s3, 3408
	s_cbranch_scc1 .Lpa_s3_j9
	s_cmp_ge_u32 s3, 3392
	s_cbranch_scc1 .Lpa_s3_j8
	s_cmp_ge_u32 s3, 3328
	s_cbranch_scc1 .Lpa_s3_j7
	s_cmp_ge_u32 s3, 2304
	s_cbranch_scc1 .Lpa_s3_j6
	s_cmp_ge_u32 s3, 1280
	s_cbranch_scc1 .Lpa_s3_j5
	s_cmp_ge_u32 s3, 1024
	s_cbranch_scc1 .Lpa_s3_j4
	s_cmp_ge_u32 s3, 768
	s_cbranch_scc1 .Lpa_s3_j3
	s_cmp_ge_u32 s3, 512
	s_cbranch_scc1 .Lpa_s3_j2
	s_cmp_ge_u32 s3, 256
	s_cbranch_scc1 .Lpa_s3_j1
	s_branch .Lpa_s3_j0

.Lpa_s3_gd:
	s_add_u32 s100, s94, 6
	s_lshl_b32 s100, s3, s100
	s_lshl_b32 s101, s28, 1
	s_add_u32 s100, s100, s101
	s_add_u32 s100, s100, s97
	s_add_u32 s90, s34, s100
	s_addc_u32 s91, s35, 0
	global_load_dword v34, v4, s[88:89] nt
	s_add_u32 s88, s88, s95
	s_addc_u32 s89, s89, 0
	global_load_dword v35, v4, s[88:89] nt
	s_add_u32 s88, s88, s95
	s_addc_u32 s89, s89, 0
	global_load_dword v36, v4, s[88:89] nt
	s_add_u32 s88, s88, s95
	s_addc_u32 s89, s89, 0
	global_load_dword v37, v4, s[88:89] nt
	s_add_u32 s88, s88, s95
	s_addc_u32 s89, s89, 0
	global_load_dword v38, v4, s[88:89] nt
	s_add_u32 s88, s88, s95
	s_addc_u32 s89, s89, 0
	global_load_dword v39, v4, s[88:89] nt
	s_add_u32 s88, s88, s95
	s_addc_u32 s89, s89, 0
	global_load_dword v40, v4, s[88:89] nt
	s_add_u32 s88, s88, s95
	s_addc_u32 s89, s89, 0
	global_load_dword v41, v4, s[88:89] nt
	s_waitcnt lgkmcnt(0)
	s_waitcnt vmcnt(24)
	v_mul_f32_e32 v10, s4, v10
	v_mul_f32_e32 v11, s5, v11
	v_mul_f32_e32 v12, s6, v12
	v_mul_f32_e32 v13, s7, v13
	v_mul_f32_e32 v14, s8, v14
	v_mul_f32_e32 v15, s9, v15
	v_mul_f32_e32 v16, s10, v16
	v_mul_f32_e32 v17, s11, v17
	v_cvt_pk_bf16_f32 v44, v10, v11
	v_cvt_pk_bf16_f32 v45, v12, v13
	v_cvt_pk_bf16_f32 v46, v14, v15
	v_cvt_pk_bf16_f32 v47, v16, v17
	v_cndmask_b32_e64 v7, v2, v5, s[64:65]
	v_lshlrev_b32_e32 v7, s66, v7
	global_store_dwordx4 v7, v[44:47], s[62:63]
	s_waitcnt vmcnt(17)
	v_mul_f32_e32 v18, s12, v18
	v_mul_f32_e32 v19, s13, v19
	v_mul_f32_e32 v20, s14, v20
	v_mul_f32_e32 v21, s15, v21
	v_mul_f32_e32 v22, s16, v22
	v_mul_f32_e32 v23, s17, v23
	v_mul_f32_e32 v24, s18, v24
	v_mul_f32_e32 v25, s19, v25
	v_cvt_pk_bf16_f32 v48, v18, v19
	v_cvt_pk_bf16_f32 v49, v20, v21
	v_cvt_pk_bf16_f32 v50, v22, v23
	v_cvt_pk_bf16_f32 v51, v24, v25
	v_cndmask_b32_e64 v7, v2, v5, s[72:73]
	v_lshlrev_b32_e32 v7, s74, v7
	global_store_dwordx4 v7, v[48:51], s[70:71]
	s_waitcnt vmcnt(10)
	v_mul_f32_e32 v26, s20, v26
	v_mul_f32_e32 v27, s21, v27
	v_mul_f32_e32 v28, s22, v28
	v_mul_f32_e32 v29, s23, v29
	v_mul_f32_e32 v30, s24, v30
	v_mul_f32_e32 v31, s25, v31
	v_mul_f32_e32 v32, s26, v32
	v_mul_f32_e32 v33, s27, v33
	v_cvt_pk_bf16_f32 v52, v26, v27
	v_cvt_pk_bf16_f32 v53, v28, v29
	v_cvt_pk_bf16_f32 v54, v30, v31
	v_cvt_pk_bf16_f32 v55, v32, v33
	v_cndmask_b32_e64 v7, v2, v5, s[80:81]
	v_lshlrev_b32_e32 v7, s82, v7
	global_store_dwordx4 v7, v[52:55], s[78:79]
	s_waitcnt vmcnt(3)
	v_mul_f32_e32 v34, s52, v34
	v_mul_f32_e32 v35, s53, v35
	v_mul_f32_e32 v36, s54, v36
	v_mul_f32_e32 v37, s55, v37
	v_mul_f32_e32 v38, s56, v38
	v_mul_f32_e32 v39, s57, v39
	v_mul_f32_e32 v40, s58, v40
	v_mul_f32_e32 v41, s59, v41
	v_cvt_pk_bf16_f32 v56, v34, v35
	v_cvt_pk_bf16_f32 v57, v36, v37
	v_cvt_pk_bf16_f32 v58, v38, v39
	v_cvt_pk_bf16_f32 v59, v40, v41
	v_cndmask_b32_e64 v7, v2, v5, s[92:93]
	v_lshlrev_b32_e32 v7, s94, v7
	global_store_dwordx4 v7, v[56:59], s[90:91]
	s_add_u32 s84, s84, 1
	s_lshl_b32 s0, s84, 2
	s_mul_i32 s0, s0, s86
	s_add_u32 s0, s0, s2
	s_cmp_lt_u32 s0, 6480
	s_cbranch_scc1 .Lpa_loop
	v_writelane_b32 v254, s86, 40
	s_nop 1
	v_writelane_b32 v254, s87, 41

.LBB0_535:
	v_add_co_u32_e32 v18, vcc, 0xffffd000, v56
	s_nop 1
	v_addc_co_u32_e32 v19, vcc, -1, v57, vcc
	global_load_dwordx4 v[70:73], v[18:19], off offset:-3072 nt
	global_load_dwordx4 v[74:77], v[18:19], off offset:-2048 nt
	global_load_dwordx4 v[78:81], v[18:19], off offset:-1024 nt
	global_load_dwordx4 v[82:85], v[18:19], off nt
	global_load_dwordx4 v[6:9], v[56:57], off offset:-3072 nt
	s_waitcnt lgkmcnt(0)
	global_load_dwordx4 v[2:5], v[56:57], off offset:-2048 nt
	global_load_dwordx4 v[14:17], v[56:57], off offset:-1024 nt
	global_load_dwordx4 v[10:13], v[56:57], off nt
	v_add_co_u32_e32 v18, vcc, 0xffffe000, v56
	s_waitcnt vmcnt(0)
	v_mul_f32_e32 v51, v71, v71
	v_addc_co_u32_e32 v19, vcc, -1, v57, vcc
	v_add_co_u32_e32 v58, vcc, 0xfffff000, v56
	global_load_dwordx4 v[46:49], v[18:19], off offset:-3072 nt
	global_load_dwordx4 v[42:45], v[18:19], off offset:-2048 nt
	global_load_dwordx4 v[38:41], v[18:19], off offset:-1024 nt
	global_load_dwordx4 v[34:37], v[18:19], off nt
	v_addc_co_u32_e32 v59, vcc, -1, v57, vcc
	global_load_dwordx4 v[30:33], v[58:59], off offset:-3072 nt
	global_load_dwordx4 v[26:29], v[58:59], off offset:-2048 nt
	global_load_dwordx4 v[22:25], v[58:59], off offset:-1024 nt
	global_load_dwordx4 v[18:21], v[56:57], off offset:-4096 nt
	v_mul_f32_e32 v58, v73, v73
	v_mul_f32_e32 v59, v75, v75
	v_mul_f32_e32 v60, v77, v77
	v_mul_f32_e32 v61, v79, v79
	v_mul_f32_e32 v86, v81, v81
	v_fmac_f32_e32 v51, v70, v70
	v_fmac_f32_e32 v58, v72, v72
	v_fmac_f32_e32 v59, v74, v74
	v_fmac_f32_e32 v60, v76, v76
	v_mul_f32_e32 v87, v83, v83
	v_mul_f32_e32 v88, v85, v85
	v_fmac_f32_e32 v61, v78, v78
	v_fmac_f32_e32 v86, v80, v80
	v_add_f32_e32 v51, v51, v58
	v_add_f32_e32 v58, v59, v60
	v_fmac_f32_e32 v87, v82, v82
	v_fmac_f32_e32 v88, v84, v84
	v_add_f32_e32 v59, v61, v86
	v_add_f32_e32 v51, v51, v58
	v_add_f32_e32 v51, v51, v59
	v_add_f32_e32 v58, v87, v88
	v_add_f32_e32 v51, v51, v58
	ds_bpermute_b32 v58, v64, v51
	v_cvt_pk_bf16_f32 v87, v72, v73
	v_cvt_pk_bf16_f32 v72, v74, v75
	v_cvt_pk_bf16_f32 v73, v76, v77
	v_cvt_pk_bf16_f32 v74, v78, v79
	s_waitcnt lgkmcnt(0)
	v_add_f32_e32 v51, v51, v58
	ds_bpermute_b32 v60, v65, v51
	v_lshl_add_u64 v[58:59], s[34:35], 0, v[54:55]
	v_cvt_pk_bf16_f32 v75, v80, v81
	v_cvt_pk_bf16_f32 v76, v82, v83
	v_cvt_pk_bf16_f32 v77, v84, v85
	s_waitcnt lgkmcnt(0)
	v_add_f32_e32 v51, v51, v60
	ds_bpermute_b32 v86, v66, v51
	v_add_co_u32_e32 v60, vcc, s3, v58
	s_waitcnt lgkmcnt(0)
	v_add_f32_e32 v51, v51, v86
	ds_bpermute_b32 v88, v67, v51
	v_cvt_pk_bf16_f32 v86, v70, v71
	v_addc_co_u32_e32 v61, vcc, 0, v59, vcc
	global_store_dwordx2 v[60:61], v[86:87], off
	global_store_dwordx2 v[60:61], v[72:73], off offset:512
	global_store_dwordx2 v[60:61], v[74:75], off offset:1024
	global_store_dwordx2 v[60:61], v[76:77], off offset:1536
	s_waitcnt lgkmcnt(0)
	v_add_f32_e32 v51, v51, v88
	ds_bpermute_b32 v70, v68, v51
	s_waitcnt lgkmcnt(0)
	v_add_f32_e32 v51, v51, v70
	ds_bpermute_b32 v70, v69, v51
	s_and_saveexec_b64 s[18:19], s[0:1]
	s_cbranch_execz .LBB0_537
	v_lshl_add_u64 v[72:73], s[34:35], 0, v[52:53]
	s_waitcnt lgkmcnt(0)
	v_add_f32_e32 v51, v51, v70
	v_add_co_u32_e32 v70, vcc, 0x1fc80000, v72
	s_nop 1
	v_addc_co_u32_e32 v71, vcc, 0, v73, vcc
	global_store_dword v[70:71], v51, off

.LBB0_559:
	v_lshl_add_u64 v[4:5], s[4:5], 0, v[2:3]
	global_load_dword v7, v[4:5], off nt
	v_add_co_u32_e32 v4, vcc, 0x1000, v4
	v_add_u32_e32 v6, s8, v6
	s_nop 0
	v_addc_co_u32_e32 v5, vcc, 0, v5, vcc
	global_load_dword v4, v[4:5], off nt
	v_cmp_lt_i32_e32 vcc, s3, v6
	s_or_b64 s[12:13], vcc, s[12:13]
	s_waitcnt vmcnt(0)
	v_sub_f32_e32 v4, v7, v4
	v_mul_f32_e32 v4, 0xbfb8aa3b, v4
	v_exp_f32_e32 v7, v4
	v_lshl_add_u64 v[4:5], s[6:7], 0, v[2:3]
	v_lshl_add_u64 v[2:3], v[2:3], 0, s[10:11]
	v_add_f32_e32 v7, 1.0, v7
	v_rcp_f32_e32 v7, v7
	global_store_dword v[4:5], v7, off
	s_andn2_b64 exec, exec, s[12:13]
	s_cbranch_execnz .LBB0_559
.LBB0_560:
	s_or_b64 exec, exec, s[0:1]
	s_cmp_lg_u64 s[34:35], 0
	s_cbranch_scc1 .LBB0_572
	v_lshrrev_b32_e32 v2, 20, v0
	v_lshrrev_b32_e32 v0, 10, v0
	v_or_b32_e32 v0, v0, v2
	s_movk_i32 s0, 0x3ff
	v_and_or_b32 v0, v0, s0, v1
	v_cmp_eq_u32_e32 vcc, 0, v0
	s_waitcnt lgkmcnt(0)
	s_barrier
	s_and_saveexec_b64 s[0:1], vcc
	s_cbranch_execz .LBB0_571
	v_readlane_b32 s4, v254, 0
	v_readlane_b32 s5, v254, 1
	buffer_wbl2 sc1
	s_waitcnt vmcnt(0)
	s_load_dwordx2 s[4:5], s[4:5], 0x58
	v_mov_b32_e32 v2, 0
	s_mov_b64 s[6:7], exec
	v_mbcnt_lo_u32_b32 v1, s6, 0
	v_mbcnt_hi_u32_b32 v1, s7, v1
	s_waitcnt lgkmcnt(0)
	global_load_dword v0, v2, s[4:5] offset:40 nt
	v_cmp_eq_u32_e32 vcc, 0, v1
	s_and_saveexec_b64 s[8:9], vcc
	s_cbranch_execz .LBB0_564
	s_bcnt1_i32_b64 s3, s[6:7]
	v_mov_b32_e32 v3, s3
	global_atomic_add v3, v2, v3, s[4:5] offset:32 sc0
